# attention work remapped so class blockIdx%8 owns tokens 2048c..: ATT->WO seam XCD-local too (4 local seams)
# speedup vs baseline: 1.0030x; 1.0030x over previous
.LBB0_770:
	s_cmp_lt_i32 s56, 12
	s_cselect_b64 s[6:7], -1, 0
	s_and_b64 s[0:1], s[6:7], s[4:5]
	s_andn2_b64 vcc, exec, s[0:1]
	s_cbranch_vccnz .LBB0_796
	s_cmpk_gt_i32 s2, 0xff
	v_mbcnt_lo_u32_b32 v115, -1, 0
	v_mbcnt_hi_u32_b32 v115, -1, v115
	s_cbranch_scc1 .LBB0_796
	v_readlane_b32 s4, v248, 0
	s_bfe_u32 s0, s4, 0x20006
	s_lshr_b32 s1, s4, 3
	s_andn2_b32 s4, s4, 63
	v_add_u32_e32 v0, s4, v115
	v_ashrrev_i32_e32 v108, 3, v0
	v_lshlrev_b32_e32 v0, 3, v115
	v_and_b32_e32 v110, 56, v0
	v_mov_b32_e32 v0, 0
	v_lshlrev_b32_e32 v2, 1, v110
	s_waitcnt vmcnt(0)
	v_mov_b32_e32 v3, v0
	v_lshl_add_u64 v[2:3], s[54:55], 0, v[2:3]
	s_mov_b64 s[4:5], 0x20000000
	v_lshl_add_u64 v[112:113], v[2:3], 0, s[4:5]
	s_movk_i32 s4, 0x308
	v_ashrrev_i32_e32 v140, 5, v115
	s_waitcnt lgkmcnt(0)
	v_mul_lo_u32 v1, v108, s4
	v_and_b32_e32 v114, 31, v115
	v_lshlrev_b32_e32 v2, 3, v140
	v_lshlrev_b32_e32 v4, 2, v140
	s_and_b32 s1, s1, 0x1fffffe0
	v_add_u32_e32 v121, 0, v1
	v_ashrrev_i32_e32 v3, 31, v2
	v_cmp_gt_u32_e32 vcc, 32, v115
	v_mul_u32_u24_e32 v1, 0x308, v114
	v_ashrrev_i32_e32 v5, 31, v4
	v_ashrrev_i32_e32 v109, 31, v108
	s_mov_b32 s11, 0
	v_lshl_add_u64 v[116:117], v[2:3], 1, s[38:39]
	v_cndmask_b32_e64 v141, 0, 1.0, vcc
	v_add_u32_e32 v142, 2, v140
	v_add_u32_e32 v143, 4, v140
	v_add_u32_e32 v144, 6, v140
	v_add3_u32 v145, 0, v2, v1
	v_lshl_add_u64 v[118:119], v[4:5], 1, s[42:43]
	v_mov_b32_e32 v120, v108
	v_mov_b32_e32 v111, v108
	v_sub_u32_e32 v146, v4, v114
	s_add_i32 s18, s1, 0x100
	s_lshl_b32 s19, s2, 9
	s_lshl_b32 s20, s58, 9
	v_lshlrev_b32_e32 v122, 1, v110
	v_mov_b32_e32 v123, v0
	s_mov_b32 s21, 0xc000
	s_movk_i32 s22, 0xfefe
	v_mov_b32_e32 v147, 0xf149f2ca
	s_and_b32 s23, s2, 7
	s_lshr_b32 s24, s2, 3
	s_lshr_b32 s12, s23, 1
	s_lshl_b32 s12, s12, 6
	s_and_b32 s23, s23, 1
	s_lshl_b32 s23, s23, 2
	s_or_b32 s23, s23, s12
	s_and_b32 s12, s24, 7
	s_lshl_b32 s12, s12, 3
	s_or_b32 s23, s23, s12
	s_lshr_b32 s24, s24, 3
	s_or_b32 s23, s23, s24
	s_lshl_b32 s19, s23, 9
	s_branch .LBB0_774
